# attnA main loop rewritten by hand: half-tile software pipeline (QK(h) | PV(h-1)+exp(h) | sum+pack(h)), K-row permutation removes permlane swaps, 1 barrier per tile
# speedup vs baseline: 1.0632x; 1.0632x over previous
.LBB0_478:
	v_mov_b32_e32 v246, v14
	v_mov_b32_e32 v247, v3
	v_mov_b32_e32 v248, v1
	v_mov_b32_e32 v249, v15
	s_add_u32 s42, s0, 0x4000
	s_addc_u32 s43, s1, 0
	s_add_u32 s44, s8, 0x4000
	s_addc_u32 s45, s9, 0
	s_waitcnt vmcnt(0)
	v_mov_b32_e32 v1, v4
	v_mov_b32_e32 v3, v5
	v_pk_add_f32 v[0:1], v[0:1], v[2:3]
	s_mov_b32 s9, 0xf800000
	v_mul_f32_e32 v0, v0, v1
	v_mul_f32_e32 v1, 0x4f800000, v0
	v_cmp_gt_f32_e32 vcc, s9, v0
	s_lshr_b32 s0, s21, 8
	s_lshl_b32 s1, s20, 20
	v_cndmask_b32_e32 v0, v0, v1, vcc
	v_sqrt_f32_e32 v1, v0
	s_and_b32 s0, s0, 1
	s_and_b32 s1, s1, 0xe00000
	s_lshl_b32 s0, s0, 20
	v_add_u32_e32 v2, -1, v1
	v_fma_f32 v3, -v2, v1, v0
	s_or_b32 s9, s1, s0
	v_cmp_ge_f32_e64 s[0:1], 0, v3
	v_add_u32_e32 v3, 1, v1
	v_lshl_or_b32 v4, s2, 7, v194
	v_cndmask_b32_e64 v2, v1, v2, s[0:1]
	v_fma_f32 v1, -v3, v1, v0
	v_cmp_lt_f32_e64 s[0:1], 0, v1
	v_and_b32_e32 v166, 63, v165
	v_or_b32_e32 v5, 32, v4
	v_cndmask_b32_e64 v1, v2, v3, s[0:1]
	v_mul_f32_e32 v2, 0x37800000, v1
	v_cndmask_b32_e32 v1, v1, v2, vcc
	v_cmp_class_f32_e32 vcc, v0, v227
	v_lshlrev_b32_e32 v2, 8, v163
	v_and_b32_e32 v3, 0xf0, v9
	v_cndmask_b32_e32 v0, v1, v0, vcc
	v_mul_f32_e32 v0, 0x3e38aa3b, v0
	s_lshl_b32 s8, s2, 6
	v_fmamk_f32 v0, v0, 0x3f8147ae, v228
	v_lshlrev_b32_e32 v1, 1, v166
	v_bitop3_b32 v167, v4, v2, v3 bitop3:0xde
	v_bitop3_b32 v168, v5, v2, v3 bitop3:0xde
	v_or_b32_e32 v5, 64, v4
	v_or_b32_e32 v4, 0x60, v4
	v_xor_b32_e32 v64, 0x80000000, v0
	v_lshlrev_b32_e32 v0, 4, v166
	v_bitop3_b32 v169, v5, v2, v3 bitop3:0xde
	v_bitop3_b32 v170, v4, v2, v3 bitop3:0xde
	v_lshlrev_b32_e32 v2, 3, v166
	v_and_b32_e32 v1, 32, v1
	s_movk_i32 s0, 0x118
	s_cmp_lg_u32 0, -1
	v_and_b32_e32 v0, 0xc0, v0
	v_and_or_b32 v1, v2, s0, v1
	s_cselect_b32 s0, 0, 0
	v_add3_u32 v171, v0, s0, v1
	s_lshl_b32 s0, s24, 1
	v_add3_u32 v0, v11, v8, s27
	s_and_b32 s0, s0, 0x80
	v_lshl_or_b32 v0, v0, 8, s0
	v_lshlrev_b32_e32 v2, 6, v164
	s_add_u32 s0, s76, s9
	v_or3_b32 v0, v0, v2, v7
	v_mov_b32_e32 v1, v195
	s_addc_u32 s1, s77, 0
	s_lshl_b32 s9, s28, 6
	v_lshl_add_u64 v[128:129], s[0:1], 0, v[0:1]
	v_add3_u32 v0, v13, v8, s29
	s_and_b32 s9, s9, 0x80
	v_lshl_or_b32 v0, v0, 8, s9
	v_or3_b32 v0, v0, v2, v7
	v_lshlrev_b32_e32 v2, 8, v6
	v_lshl_add_u64 v[130:131], s[0:1], 0, v[0:1]
	v_add3_u32 v0, s30, v2, v10
	s_addk_i32 s30, 0x2000
	v_mov_b32_e32 v136, 0
	v_lshl_add_u64 v[132:133], s[0:1], 0, v[0:1]
	v_add3_u32 v0, s30, v2, v12
	v_mov_b32_e32 v65, v64
	v_mov_b32_e32 v66, v64
	v_mov_b32_e32 v67, v64
	v_mov_b32_e32 v68, v64
	v_mov_b32_e32 v69, v64
	v_mov_b32_e32 v70, v64
	v_mov_b32_e32 v71, v64
	v_mov_b32_e32 v72, v64
	v_mov_b32_e32 v73, v64
	v_mov_b32_e32 v74, v64
	v_mov_b32_e32 v75, v64
	v_mov_b32_e32 v76, v64
	v_mov_b32_e32 v77, v64
	v_mov_b32_e32 v78, v64
	v_mov_b32_e32 v79, v64
	v_lshl_add_u64 v[134:135], s[0:1], 0, v[0:1]
	s_mov_b32 s9, 0x18000
	s_mov_b64 s[0:1], 0
	v_mov_b32_e32 v48, 0
	v_mov_b32_e32 v49, v136
	v_mov_b32_e32 v50, v136
	v_mov_b32_e32 v51, v136
	v_mov_b32_e32 v52, v136
	v_mov_b32_e32 v53, v136
	v_mov_b32_e32 v54, v136
	v_mov_b32_e32 v55, v136
	v_mov_b32_e32 v56, v136
	v_mov_b32_e32 v57, v136
	v_mov_b32_e32 v58, v136
	v_mov_b32_e32 v59, v136
	v_mov_b32_e32 v60, v136
	v_mov_b32_e32 v61, v136
	v_mov_b32_e32 v62, v136
	v_mov_b32_e32 v63, v136
	v_mov_b32_e32 v32, 0
	v_mov_b32_e32 v33, v136
	v_mov_b32_e32 v34, v136
	v_mov_b32_e32 v35, v136
	v_mov_b32_e32 v36, v136
	v_mov_b32_e32 v37, v136
	v_mov_b32_e32 v38, v136
	v_mov_b32_e32 v39, v136
	v_mov_b32_e32 v40, v136
	v_mov_b32_e32 v41, v136
	v_mov_b32_e32 v42, v136
	v_mov_b32_e32 v43, v136
	v_mov_b32_e32 v44, v136
	v_mov_b32_e32 v45, v136
	v_mov_b32_e32 v46, v136
	v_mov_b32_e32 v47, v136
	v_mov_b32_e32 v16, 0
	v_mov_b32_e32 v17, v136
	v_mov_b32_e32 v18, v136
	v_mov_b32_e32 v19, v136
	v_mov_b32_e32 v20, v136
	v_mov_b32_e32 v21, v136
	v_mov_b32_e32 v22, v136
	v_mov_b32_e32 v23, v136
	v_mov_b32_e32 v24, v136
	v_mov_b32_e32 v25, v136
	v_mov_b32_e32 v26, v136
	v_mov_b32_e32 v27, v136
	v_mov_b32_e32 v28, v136
	v_mov_b32_e32 v29, v136
	v_mov_b32_e32 v30, v136
	v_mov_b32_e32 v31, v136
	v_mov_b32_e32 v0, 0
	v_mov_b32_e32 v1, v136
	v_mov_b32_e32 v2, v136
	v_mov_b32_e32 v3, v136
	v_mov_b32_e32 v4, v136
	v_mov_b32_e32 v5, v136
	v_mov_b32_e32 v6, v136
	v_mov_b32_e32 v7, v136
	v_mov_b32_e32 v8, v136
	v_mov_b32_e32 v9, v136
	v_mov_b32_e32 v10, v136
	v_mov_b32_e32 v11, v136
	v_mov_b32_e32 v12, v136
	v_mov_b32_e32 v13, v136
	v_mov_b32_e32 v14, v136
	v_mov_b32_e32 v15, v136
	s_bfe_u32 s49, s24, 0x10006
	s_lshl_b32 s49, s49, 7
	v_and_b32_e32 v156, 0x13, v163
	v_and_b32_e32 v157, 4, v163
	v_and_b32_e32 v158, 8, v163
	v_lshlrev_b32_e32 v157, 1, v157
	v_lshrrev_b32_e32 v158, 1, v158
	v_or3_b32 v156, v156, v157, v158
	v_and_b32_e32 v157, 15, v156
	v_lshlrev_b32_e32 v157, 4, v157
	v_lshlrev_b32_e32 v156, 8, v156
	v_lshlrev_b32_e32 v158, 4, v164
	v_add_u32_e32 v158, s49, v158
	v_add_u32_e32 v159, 0, v158
	v_xor_b32_e32 v159, v159, v157
	v_add_u32_e32 v236, v159, v156
	v_add_u32_e32 v240, 0x10000, v236
	v_add_u32_e32 v159, 32, v158
	v_xor_b32_e32 v159, v159, v157
	v_add_u32_e32 v237, v159, v156
	v_add_u32_e32 v241, 0x10000, v237
	v_add_u32_e32 v159, 64, v158
	v_xor_b32_e32 v159, v159, v157
	v_add_u32_e32 v238, v159, v156
	v_add_u32_e32 v242, 0x10000, v238
	v_add_u32_e32 v159, 96, v158
	v_xor_b32_e32 v159, v159, v157
	v_add_u32_e32 v239, v159, v156
	v_add_u32_e32 v243, 0x10000, v239
	v_add_u32_e32 v244, 0x10000, v171
	v_mov_b32_e32 v96, 0
	v_mov_b32_e32 v97, 0
	v_mov_b32_e32 v98, 0
	v_mov_b32_e32 v99, 0
	v_mov_b32_e32 v100, 0
	v_mov_b32_e32 v101, 0
	v_mov_b32_e32 v102, 0
	v_mov_b32_e32 v103, 0
	v_mov_b32_e32 v104, 0
	v_mov_b32_e32 v105, 0
	v_mov_b32_e32 v106, 0
	v_mov_b32_e32 v107, 0
	v_mov_b32_e32 v108, 0
	v_mov_b32_e32 v109, 0
	v_mov_b32_e32 v110, 0
	v_mov_b32_e32 v111, 0
	v_mov_b32_e32 v137, 0
	s_add_i32 m0, s25, 0x10000
	s_nop 0
	global_load_lds_dwordx4 v246, s[42:43]
	s_add_i32 m0, s25, 0x14000
	s_nop 0
	global_load_lds_dwordx4 v247, s[44:45]
	s_add_i32 m0, s25, 0x12000
	s_nop 0
	global_load_lds_dwordx4 v248, s[42:43]
	s_add_i32 m0, s25, 0x16000
	s_nop 0
	global_load_lds_dwordx4 v249, s[44:45]
	s_add_u32 s42, s42, 0x4000
	s_addc_u32 s43, s43, 0
	s_add_u32 s44, s44, 0x4000
	s_addc_u32 s45, s45, 0
	s_waitcnt vmcnt(4)
	s_barrier
	ds_read_b128 v[140:143], v236 offset:16384
	ds_read_b128 v[144:147], v237 offset:16384
	ds_read_b128 v[148:151], v238 offset:16384
	ds_read_b128 v[152:155], v239 offset:16384
	ds_read_b64_tr_b16 v[172:173], v171 offset:0
	ds_read_b64_tr_b16 v[174:175], v171 offset:2048
	ds_read_b64_tr_b16 v[176:177], v171 offset:512
	ds_read_b64_tr_b16 v[178:179], v171 offset:2560
	ds_read_b64_tr_b16 v[180:181], v171 offset:1024
	ds_read_b64_tr_b16 v[182:183], v171 offset:3072
	ds_read_b64_tr_b16 v[184:185], v171 offset:1536
	ds_read_b64_tr_b16 v[186:187], v171 offset:3584
	ds_read_b64_tr_b16 v[188:189], v171 offset:4096
	ds_read_b64_tr_b16 v[190:191], v171 offset:6144
	ds_read_b64_tr_b16 v[204:205], v171 offset:4608
	ds_read_b64_tr_b16 v[206:207], v171 offset:6656
	ds_read_b64_tr_b16 v[208:209], v171 offset:5120
	ds_read_b64_tr_b16 v[210:211], v171 offset:7168
	ds_read_b64_tr_b16 v[212:213], v171 offset:5632
	ds_read_b64_tr_b16 v[214:215], v171 offset:7680
	s_mov_b32 s48, 0
.Lda_loop:
	s_waitcnt vmcnt(4)
	s_waitcnt lgkmcnt(0)
	s_barrier
	v_mfma_f32_32x32x16_bf16 v[80:95], v[140:143], v[112:115], v[64:79]
	v_add_f32_e32 v136, v96, v136
	v_add_f32_e32 v137, v97, v137
	v_add_f32_e32 v136, v98, v136
	v_add_f32_e32 v137, v99, v137
	v_cvt_pk_bf16_f32 v96, v96, v97
	v_cvt_pk_bf16_f32 v97, v98, v99
	v_mfma_f32_32x32x16_bf16 v[80:95], v[144:147], v[116:119], v[80:95]
	v_add_f32_e32 v136, v100, v136
	v_add_f32_e32 v137, v101, v137
	v_add_f32_e32 v136, v102, v136
	v_add_f32_e32 v137, v103, v137
	v_cvt_pk_bf16_f32 v98, v100, v101
	v_cvt_pk_bf16_f32 v99, v102, v103
	v_mfma_f32_32x32x16_bf16 v[80:95], v[148:151], v[120:123], v[80:95]
	v_add_f32_e32 v136, v104, v136
	v_add_f32_e32 v137, v105, v137
	v_add_f32_e32 v136, v106, v136
	v_add_f32_e32 v137, v107, v137
	v_cvt_pk_bf16_f32 v100, v104, v105
	v_cvt_pk_bf16_f32 v101, v106, v107
	v_mfma_f32_32x32x16_bf16 v[80:95], v[152:155], v[124:127], v[80:95]
	v_cvt_pk_bf16_f32 v102, v108, v109
	v_cvt_pk_bf16_f32 v103, v110, v111
	v_add_f32_e32 v136, v108, v136
	v_add_f32_e32 v137, v109, v137
	v_add_f32_e32 v136, v110, v136
	v_add_f32_e32 v137, v111, v137
	v_mfma_f32_32x32x16_bf16 v[48:63], v[96:99], v[172:175], v[48:63]
	ds_read_b128 v[140:143], v236 offset:24576
	ds_read_b128 v[144:147], v237 offset:24576
	ds_read_b64_tr_b16 v[172:173], v171 offset:0
	ds_read_b64_tr_b16 v[174:175], v171 offset:2048
	s_add_i32 m0, s25, 0x18000
	s_nop 0
	global_load_lds_dwordx4 v246, s[42:43]
	s_add_i32 m0, s25, 0x1c000
	s_nop 0
	global_load_lds_dwordx4 v247, s[44:45]
	v_mfma_f32_32x32x16_bf16 v[32:47], v[96:99], v[176:179], v[32:47]
	ds_read_b128 v[148:151], v238 offset:24576
	ds_read_b128 v[152:155], v239 offset:24576
	ds_read_b64_tr_b16 v[176:177], v171 offset:512
	ds_read_b64_tr_b16 v[178:179], v171 offset:2560
	s_add_i32 m0, s25, 0x1a000
	s_nop 0
	global_load_lds_dwordx4 v248, s[42:43]
	s_add_i32 m0, s25, 0x1e000
	s_nop 0
	global_load_lds_dwordx4 v249, s[44:45]
	v_exp_f32_e32 v80, v80
	v_exp_f32_e32 v81, v81
	v_mfma_f32_32x32x16_bf16 v[16:31], v[96:99], v[180:183], v[16:31]
	ds_read_b64_tr_b16 v[180:181], v171 offset:1024
	ds_read_b64_tr_b16 v[182:183], v171 offset:3072
	v_exp_f32_e32 v82, v82
	v_exp_f32_e32 v83, v83
	v_mfma_f32_32x32x16_bf16 v[0:15], v[96:99], v[184:187], v[0:15]
	ds_read_b64_tr_b16 v[184:185], v171 offset:1536
	ds_read_b64_tr_b16 v[186:187], v171 offset:3584
	v_exp_f32_e32 v84, v84
	v_exp_f32_e32 v85, v85
	v_mfma_f32_32x32x16_bf16 v[48:63], v[100:103], v[188:191], v[48:63]
	ds_read_b64_tr_b16 v[188:189], v171 offset:4096
	ds_read_b64_tr_b16 v[190:191], v171 offset:6144
	v_exp_f32_e32 v86, v86
	v_exp_f32_e32 v87, v87
	v_mfma_f32_32x32x16_bf16 v[32:47], v[100:103], v[204:207], v[32:47]
	ds_read_b64_tr_b16 v[204:205], v171 offset:4608
	ds_read_b64_tr_b16 v[206:207], v171 offset:6656
	v_exp_f32_e32 v88, v88
	v_exp_f32_e32 v89, v89
	v_exp_f32_e32 v90, v90
	v_mfma_f32_32x32x16_bf16 v[16:31], v[100:103], v[208:211], v[16:31]
	ds_read_b64_tr_b16 v[208:209], v171 offset:5120
	ds_read_b64_tr_b16 v[210:211], v171 offset:7168
	v_exp_f32_e32 v91, v91
	v_exp_f32_e32 v92, v92
	v_exp_f32_e32 v93, v93
	v_mfma_f32_32x32x16_bf16 v[0:15], v[100:103], v[212:215], v[0:15]
	ds_read_b64_tr_b16 v[212:213], v171 offset:5632
	ds_read_b64_tr_b16 v[214:215], v171 offset:7680
	v_exp_f32_e32 v94, v94
	v_exp_f32_e32 v95, v95
	s_add_u32 s42, s42, 0x4000
	s_addc_u32 s43, s43, 0
	s_add_u32 s44, s44, 0x4000
	s_addc_u32 s45, s45, 0
	s_waitcnt lgkmcnt(15)
	v_mfma_f32_32x32x16_bf16 v[96:111], v[140:143], v[112:115], v[64:79]
	v_add_f32_e32 v136, v80, v136
	v_add_f32_e32 v137, v81, v137
	v_add_f32_e32 v136, v82, v136
	v_add_f32_e32 v137, v83, v137
	v_cvt_pk_bf16_f32 v80, v80, v81
	v_cvt_pk_bf16_f32 v81, v82, v83
	v_mfma_f32_32x32x16_bf16 v[96:111], v[144:147], v[116:119], v[96:111]
	v_add_f32_e32 v136, v84, v136
	v_add_f32_e32 v137, v85, v137
	v_add_f32_e32 v136, v86, v136
	v_add_f32_e32 v137, v87, v137
	v_cvt_pk_bf16_f32 v82, v84, v85
	v_cvt_pk_bf16_f32 v83, v86, v87
	v_mfma_f32_32x32x16_bf16 v[96:111], v[148:151], v[120:123], v[96:111]
	v_add_f32_e32 v136, v88, v136
	v_add_f32_e32 v137, v89, v137
	v_add_f32_e32 v136, v90, v136
	v_add_f32_e32 v137, v91, v137
	v_cvt_pk_bf16_f32 v84, v88, v89
	v_cvt_pk_bf16_f32 v85, v90, v91
	s_waitcnt lgkmcnt(14)
	v_mfma_f32_32x32x16_bf16 v[96:111], v[152:155], v[124:127], v[96:111]
	v_cvt_pk_bf16_f32 v86, v92, v93
	v_cvt_pk_bf16_f32 v87, v94, v95
	v_add_f32_e32 v136, v92, v136
	v_add_f32_e32 v137, v93, v137
	v_add_f32_e32 v136, v94, v136
	v_add_f32_e32 v137, v95, v137
	v_mfma_f32_32x32x16_bf16 v[48:63], v[80:83], v[172:175], v[48:63]
	ds_read_b128 v[140:143], v236 offset:49152
	ds_read_b128 v[144:147], v237 offset:49152
	ds_read_b64_tr_b16 v[172:173], v171 offset:8192
	ds_read_b64_tr_b16 v[174:175], v171 offset:10240
	s_waitcnt lgkmcnt(15)
	v_mfma_f32_32x32x16_bf16 v[32:47], v[80:83], v[176:179], v[32:47]
	ds_read_b128 v[148:151], v238 offset:49152
	ds_read_b128 v[152:155], v239 offset:49152
	ds_read_b64_tr_b16 v[176:177], v171 offset:8704
	ds_read_b64_tr_b16 v[178:179], v171 offset:10752
	v_exp_f32_e32 v96, v96
	v_exp_f32_e32 v97, v97
	s_waitcnt lgkmcnt(15)
	v_mfma_f32_32x32x16_bf16 v[16:31], v[80:83], v[180:183], v[16:31]
	ds_read_b64_tr_b16 v[180:181], v171 offset:9216
	ds_read_b64_tr_b16 v[182:183], v171 offset:11264
	v_exp_f32_e32 v98, v98
	v_exp_f32_e32 v99, v99
	v_mfma_f32_32x32x16_bf16 v[0:15], v[80:83], v[184:187], v[0:15]
	ds_read_b64_tr_b16 v[184:185], v171 offset:9728
	ds_read_b64_tr_b16 v[186:187], v171 offset:11776
	v_exp_f32_e32 v100, v100
	v_exp_f32_e32 v101, v101
	s_waitcnt lgkmcnt(15)
	v_mfma_f32_32x32x16_bf16 v[48:63], v[84:87], v[188:191], v[48:63]
	ds_read_b64_tr_b16 v[188:189], v171 offset:12288
	ds_read_b64_tr_b16 v[190:191], v171 offset:14336
	v_exp_f32_e32 v102, v102
	v_exp_f32_e32 v103, v103
	v_mfma_f32_32x32x16_bf16 v[32:47], v[84:87], v[204:207], v[32:47]
	ds_read_b64_tr_b16 v[204:205], v171 offset:12800
	ds_read_b64_tr_b16 v[206:207], v171 offset:14848
	v_exp_f32_e32 v104, v104
	v_exp_f32_e32 v105, v105
	v_exp_f32_e32 v106, v106
	s_waitcnt lgkmcnt(15)
	v_mfma_f32_32x32x16_bf16 v[16:31], v[84:87], v[208:211], v[16:31]
	ds_read_b64_tr_b16 v[208:209], v171 offset:13312
	ds_read_b64_tr_b16 v[210:211], v171 offset:15360
	v_exp_f32_e32 v107, v107
	v_exp_f32_e32 v108, v108
	v_exp_f32_e32 v109, v109
	v_mfma_f32_32x32x16_bf16 v[0:15], v[84:87], v[212:215], v[0:15]
	ds_read_b64_tr_b16 v[212:213], v171 offset:13824
	ds_read_b64_tr_b16 v[214:215], v171 offset:15872
	v_exp_f32_e32 v110, v110
	v_exp_f32_e32 v111, v111
	s_waitcnt vmcnt(4)
	s_waitcnt lgkmcnt(0)
	s_barrier
	v_mfma_f32_32x32x16_bf16 v[80:95], v[140:143], v[112:115], v[64:79]
	v_add_f32_e32 v136, v96, v136
	v_add_f32_e32 v137, v97, v137
	v_add_f32_e32 v136, v98, v136
	v_add_f32_e32 v137, v99, v137
	v_cvt_pk_bf16_f32 v96, v96, v97
	v_cvt_pk_bf16_f32 v97, v98, v99
	v_mfma_f32_32x32x16_bf16 v[80:95], v[144:147], v[116:119], v[80:95]
	v_add_f32_e32 v136, v100, v136
	v_add_f32_e32 v137, v101, v137
	v_add_f32_e32 v136, v102, v136
	v_add_f32_e32 v137, v103, v137
	v_cvt_pk_bf16_f32 v98, v100, v101
	v_cvt_pk_bf16_f32 v99, v102, v103
	v_mfma_f32_32x32x16_bf16 v[80:95], v[148:151], v[120:123], v[80:95]
	v_add_f32_e32 v136, v104, v136
	v_add_f32_e32 v137, v105, v137
	v_add_f32_e32 v136, v106, v136
	v_add_f32_e32 v137, v107, v137
	v_cvt_pk_bf16_f32 v100, v104, v105
	v_cvt_pk_bf16_f32 v101, v106, v107
	v_mfma_f32_32x32x16_bf16 v[80:95], v[152:155], v[124:127], v[80:95]
	v_cvt_pk_bf16_f32 v102, v108, v109
	v_cvt_pk_bf16_f32 v103, v110, v111
	v_add_f32_e32 v136, v108, v136
	v_add_f32_e32 v137, v109, v137
	v_add_f32_e32 v136, v110, v136
	v_add_f32_e32 v137, v111, v137
	v_mfma_f32_32x32x16_bf16 v[48:63], v[96:99], v[172:175], v[48:63]
	ds_read_b128 v[140:143], v236 offset:57344
	ds_read_b128 v[144:147], v237 offset:57344
	ds_read_b64_tr_b16 v[172:173], v171 offset:32768
	ds_read_b64_tr_b16 v[174:175], v171 offset:34816
	s_mov_b32 m0, s25
	s_nop 0
	global_load_lds_dwordx4 v246, s[42:43]
	s_add_i32 m0, s25, 0x4000
	s_nop 0
	global_load_lds_dwordx4 v247, s[44:45]
	v_mfma_f32_32x32x16_bf16 v[32:47], v[96:99], v[176:179], v[32:47]
	ds_read_b128 v[148:151], v238 offset:57344
	ds_read_b128 v[152:155], v239 offset:57344
	ds_read_b64_tr_b16 v[176:177], v171 offset:33280
	ds_read_b64_tr_b16 v[178:179], v171 offset:35328
	s_add_i32 m0, s25, 0x2000
	s_nop 0
	global_load_lds_dwordx4 v248, s[42:43]
	s_add_i32 m0, s25, 0x6000
	s_nop 0
	global_load_lds_dwordx4 v249, s[44:45]
	v_exp_f32_e32 v80, v80
	v_exp_f32_e32 v81, v81
	v_mfma_f32_32x32x16_bf16 v[16:31], v[96:99], v[180:183], v[16:31]
	ds_read_b64_tr_b16 v[180:181], v171 offset:33792
	ds_read_b64_tr_b16 v[182:183], v171 offset:35840
	v_exp_f32_e32 v82, v82
	v_exp_f32_e32 v83, v83
	v_mfma_f32_32x32x16_bf16 v[0:15], v[96:99], v[184:187], v[0:15]
	ds_read_b64_tr_b16 v[184:185], v171 offset:34304
	ds_read_b64_tr_b16 v[186:187], v171 offset:36352
	v_exp_f32_e32 v84, v84
	v_exp_f32_e32 v85, v85
	v_mfma_f32_32x32x16_bf16 v[48:63], v[100:103], v[188:191], v[48:63]
	ds_read_b64_tr_b16 v[188:189], v171 offset:36864
	ds_read_b64_tr_b16 v[190:191], v171 offset:38912
	v_exp_f32_e32 v86, v86
	v_exp_f32_e32 v87, v87
	v_mfma_f32_32x32x16_bf16 v[32:47], v[100:103], v[204:207], v[32:47]
	ds_read_b64_tr_b16 v[204:205], v171 offset:37376
	ds_read_b64_tr_b16 v[206:207], v171 offset:39424
	v_exp_f32_e32 v88, v88
	v_exp_f32_e32 v89, v89
	v_exp_f32_e32 v90, v90
	v_mfma_f32_32x32x16_bf16 v[16:31], v[100:103], v[208:211], v[16:31]
	ds_read_b64_tr_b16 v[208:209], v171 offset:37888
	ds_read_b64_tr_b16 v[210:211], v171 offset:39936
	v_exp_f32_e32 v91, v91
	v_exp_f32_e32 v92, v92
	v_exp_f32_e32 v93, v93
	v_mfma_f32_32x32x16_bf16 v[0:15], v[100:103], v[212:215], v[0:15]
	ds_read_b64_tr_b16 v[212:213], v171 offset:38400
	ds_read_b64_tr_b16 v[214:215], v171 offset:40448
	v_exp_f32_e32 v94, v94
	v_exp_f32_e32 v95, v95
	s_add_u32 s42, s42, 0x4000
	s_addc_u32 s43, s43, 0
	s_add_u32 s44, s44, 0x4000
	s_addc_u32 s45, s45, 0
	s_waitcnt lgkmcnt(15)
	v_mfma_f32_32x32x16_bf16 v[96:111], v[140:143], v[112:115], v[64:79]
	v_add_f32_e32 v136, v80, v136
	v_add_f32_e32 v137, v81, v137
	v_add_f32_e32 v136, v82, v136
	v_add_f32_e32 v137, v83, v137
	v_cvt_pk_bf16_f32 v80, v80, v81
	v_cvt_pk_bf16_f32 v81, v82, v83
	v_mfma_f32_32x32x16_bf16 v[96:111], v[144:147], v[116:119], v[96:111]
	v_add_f32_e32 v136, v84, v136
	v_add_f32_e32 v137, v85, v137
	v_add_f32_e32 v136, v86, v136
	v_add_f32_e32 v137, v87, v137
	v_cvt_pk_bf16_f32 v82, v84, v85
	v_cvt_pk_bf16_f32 v83, v86, v87
	v_mfma_f32_32x32x16_bf16 v[96:111], v[148:151], v[120:123], v[96:111]
	v_add_f32_e32 v136, v88, v136
	v_add_f32_e32 v137, v89, v137
	v_add_f32_e32 v136, v90, v136
	v_add_f32_e32 v137, v91, v137
	v_cvt_pk_bf16_f32 v84, v88, v89
	v_cvt_pk_bf16_f32 v85, v90, v91
	s_waitcnt lgkmcnt(14)
	v_mfma_f32_32x32x16_bf16 v[96:111], v[152:155], v[124:127], v[96:111]
	v_cvt_pk_bf16_f32 v86, v92, v93
	v_cvt_pk_bf16_f32 v87, v94, v95
	v_add_f32_e32 v136, v92, v136
	v_add_f32_e32 v137, v93, v137
	v_add_f32_e32 v136, v94, v136
	v_add_f32_e32 v137, v95, v137
	v_mfma_f32_32x32x16_bf16 v[48:63], v[80:83], v[172:175], v[48:63]
	ds_read_b128 v[140:143], v240 offset:16384
	ds_read_b128 v[144:147], v241 offset:16384
	ds_read_b64_tr_b16 v[172:173], v171 offset:40960
	ds_read_b64_tr_b16 v[174:175], v171 offset:43008
	s_waitcnt lgkmcnt(15)
	v_mfma_f32_32x32x16_bf16 v[32:47], v[80:83], v[176:179], v[32:47]
	ds_read_b128 v[148:151], v242 offset:16384
	ds_read_b128 v[152:155], v243 offset:16384
	ds_read_b64_tr_b16 v[176:177], v171 offset:41472
	ds_read_b64_tr_b16 v[178:179], v171 offset:43520
	v_exp_f32_e32 v96, v96
	v_exp_f32_e32 v97, v97
	s_waitcnt lgkmcnt(15)
	v_mfma_f32_32x32x16_bf16 v[16:31], v[80:83], v[180:183], v[16:31]
	ds_read_b64_tr_b16 v[180:181], v171 offset:41984
	ds_read_b64_tr_b16 v[182:183], v171 offset:44032
	v_exp_f32_e32 v98, v98
	v_exp_f32_e32 v99, v99
	v_mfma_f32_32x32x16_bf16 v[0:15], v[80:83], v[184:187], v[0:15]
	ds_read_b64_tr_b16 v[184:185], v171 offset:42496
	ds_read_b64_tr_b16 v[186:187], v171 offset:44544
	v_exp_f32_e32 v100, v100
	v_exp_f32_e32 v101, v101
	s_waitcnt lgkmcnt(15)
	v_mfma_f32_32x32x16_bf16 v[48:63], v[84:87], v[188:191], v[48:63]
	ds_read_b64_tr_b16 v[188:189], v171 offset:45056
	ds_read_b64_tr_b16 v[190:191], v171 offset:47104
	v_exp_f32_e32 v102, v102
	v_exp_f32_e32 v103, v103
	v_mfma_f32_32x32x16_bf16 v[32:47], v[84:87], v[204:207], v[32:47]
	ds_read_b64_tr_b16 v[204:205], v171 offset:45568
	ds_read_b64_tr_b16 v[206:207], v171 offset:47616
	v_exp_f32_e32 v104, v104
	v_exp_f32_e32 v105, v105
	v_exp_f32_e32 v106, v106
	s_waitcnt lgkmcnt(15)
	v_mfma_f32_32x32x16_bf16 v[16:31], v[84:87], v[208:211], v[16:31]
	ds_read_b64_tr_b16 v[208:209], v171 offset:46080
	ds_read_b64_tr_b16 v[210:211], v171 offset:48128
	v_exp_f32_e32 v107, v107
	v_exp_f32_e32 v108, v108
	v_exp_f32_e32 v109, v109
	v_mfma_f32_32x32x16_bf16 v[0:15], v[84:87], v[212:215], v[0:15]
	ds_read_b64_tr_b16 v[212:213], v171 offset:46592
	ds_read_b64_tr_b16 v[214:215], v171 offset:48640
	v_exp_f32_e32 v110, v110
	v_exp_f32_e32 v111, v111
	s_waitcnt vmcnt(4)
	s_waitcnt lgkmcnt(0)
	s_barrier
	v_mfma_f32_32x32x16_bf16 v[80:95], v[140:143], v[112:115], v[64:79]
	v_add_f32_e32 v136, v96, v136
	v_add_f32_e32 v137, v97, v137
	v_add_f32_e32 v136, v98, v136
	v_add_f32_e32 v137, v99, v137
	v_cvt_pk_bf16_f32 v96, v96, v97
	v_cvt_pk_bf16_f32 v97, v98, v99
	v_mfma_f32_32x32x16_bf16 v[80:95], v[144:147], v[116:119], v[80:95]
	v_add_f32_e32 v136, v100, v136
	v_add_f32_e32 v137, v101, v137
	v_add_f32_e32 v136, v102, v136
	v_add_f32_e32 v137, v103, v137
	v_cvt_pk_bf16_f32 v98, v100, v101
	v_cvt_pk_bf16_f32 v99, v102, v103
	v_mfma_f32_32x32x16_bf16 v[80:95], v[148:151], v[120:123], v[80:95]
	v_add_f32_e32 v136, v104, v136
	v_add_f32_e32 v137, v105, v137
	v_add_f32_e32 v136, v106, v136
	v_add_f32_e32 v137, v107, v137
	v_cvt_pk_bf16_f32 v100, v104, v105
	v_cvt_pk_bf16_f32 v101, v106, v107
	v_mfma_f32_32x32x16_bf16 v[80:95], v[152:155], v[124:127], v[80:95]
	v_cvt_pk_bf16_f32 v102, v108, v109
	v_cvt_pk_bf16_f32 v103, v110, v111
	v_add_f32_e32 v136, v108, v136
	v_add_f32_e32 v137, v109, v137
	v_add_f32_e32 v136, v110, v136
	v_add_f32_e32 v137, v111, v137
	v_mfma_f32_32x32x16_bf16 v[48:63], v[96:99], v[172:175], v[48:63]
	ds_read_b128 v[140:143], v240 offset:24576
	ds_read_b128 v[144:147], v241 offset:24576
	ds_read_b64_tr_b16 v[172:173], v244 offset:0
	ds_read_b64_tr_b16 v[174:175], v244 offset:2048
	s_add_i32 m0, s25, 0x8000
	s_nop 0
	global_load_lds_dwordx4 v246, s[42:43]
	s_add_i32 m0, s25, 0xc000
	s_nop 0
	global_load_lds_dwordx4 v247, s[44:45]
	v_mfma_f32_32x32x16_bf16 v[32:47], v[96:99], v[176:179], v[32:47]
	ds_read_b128 v[148:151], v242 offset:24576
	ds_read_b128 v[152:155], v243 offset:24576
	ds_read_b64_tr_b16 v[176:177], v244 offset:512
	ds_read_b64_tr_b16 v[178:179], v244 offset:2560
	s_add_i32 m0, s25, 0xa000
	s_nop 0
	global_load_lds_dwordx4 v248, s[42:43]
	s_add_i32 m0, s25, 0xe000
	s_nop 0
	global_load_lds_dwordx4 v249, s[44:45]
	v_exp_f32_e32 v80, v80
	v_exp_f32_e32 v81, v81
	v_mfma_f32_32x32x16_bf16 v[16:31], v[96:99], v[180:183], v[16:31]
	ds_read_b64_tr_b16 v[180:181], v244 offset:1024
	ds_read_b64_tr_b16 v[182:183], v244 offset:3072
	v_exp_f32_e32 v82, v82
	v_exp_f32_e32 v83, v83
	v_mfma_f32_32x32x16_bf16 v[0:15], v[96:99], v[184:187], v[0:15]
	ds_read_b64_tr_b16 v[184:185], v244 offset:1536
	ds_read_b64_tr_b16 v[186:187], v244 offset:3584
	v_exp_f32_e32 v84, v84
	v_exp_f32_e32 v85, v85
	v_mfma_f32_32x32x16_bf16 v[48:63], v[100:103], v[188:191], v[48:63]
	ds_read_b64_tr_b16 v[188:189], v244 offset:4096
	ds_read_b64_tr_b16 v[190:191], v244 offset:6144
	v_exp_f32_e32 v86, v86
	v_exp_f32_e32 v87, v87
	v_mfma_f32_32x32x16_bf16 v[32:47], v[100:103], v[204:207], v[32:47]
	ds_read_b64_tr_b16 v[204:205], v244 offset:4608
	ds_read_b64_tr_b16 v[206:207], v244 offset:6656
	v_exp_f32_e32 v88, v88
	v_exp_f32_e32 v89, v89
	v_exp_f32_e32 v90, v90
	v_mfma_f32_32x32x16_bf16 v[16:31], v[100:103], v[208:211], v[16:31]
	ds_read_b64_tr_b16 v[208:209], v244 offset:5120
	ds_read_b64_tr_b16 v[210:211], v244 offset:7168
	v_exp_f32_e32 v91, v91
	v_exp_f32_e32 v92, v92
	v_exp_f32_e32 v93, v93
	v_mfma_f32_32x32x16_bf16 v[0:15], v[100:103], v[212:215], v[0:15]
	ds_read_b64_tr_b16 v[212:213], v244 offset:5632
	ds_read_b64_tr_b16 v[214:215], v244 offset:7680
	v_exp_f32_e32 v94, v94
	v_exp_f32_e32 v95, v95
	s_add_u32 s42, s42, 0x4000
	s_addc_u32 s43, s43, 0
	s_add_u32 s44, s44, 0x4000
	s_addc_u32 s45, s45, 0
	s_waitcnt lgkmcnt(15)
	v_mfma_f32_32x32x16_bf16 v[96:111], v[140:143], v[112:115], v[64:79]
	v_add_f32_e32 v136, v80, v136
	v_add_f32_e32 v137, v81, v137
	v_add_f32_e32 v136, v82, v136
	v_add_f32_e32 v137, v83, v137
	v_cvt_pk_bf16_f32 v80, v80, v81
	v_cvt_pk_bf16_f32 v81, v82, v83
	v_mfma_f32_32x32x16_bf16 v[96:111], v[144:147], v[116:119], v[96:111]
	v_add_f32_e32 v136, v84, v136
	v_add_f32_e32 v137, v85, v137
	v_add_f32_e32 v136, v86, v136
	v_add_f32_e32 v137, v87, v137
	v_cvt_pk_bf16_f32 v82, v84, v85
	v_cvt_pk_bf16_f32 v83, v86, v87
	v_mfma_f32_32x32x16_bf16 v[96:111], v[148:151], v[120:123], v[96:111]
	v_add_f32_e32 v136, v88, v136
	v_add_f32_e32 v137, v89, v137
	v_add_f32_e32 v136, v90, v136
	v_add_f32_e32 v137, v91, v137
	v_cvt_pk_bf16_f32 v84, v88, v89
	v_cvt_pk_bf16_f32 v85, v90, v91
	s_waitcnt lgkmcnt(14)
	v_mfma_f32_32x32x16_bf16 v[96:111], v[152:155], v[124:127], v[96:111]
	v_cvt_pk_bf16_f32 v86, v92, v93
	v_cvt_pk_bf16_f32 v87, v94, v95
	v_add_f32_e32 v136, v92, v136
	v_add_f32_e32 v137, v93, v137
	v_add_f32_e32 v136, v94, v136
	v_add_f32_e32 v137, v95, v137
	v_mfma_f32_32x32x16_bf16 v[48:63], v[80:83], v[172:175], v[48:63]
	ds_read_b128 v[140:143], v240 offset:49152
	ds_read_b128 v[144:147], v241 offset:49152
	ds_read_b64_tr_b16 v[172:173], v244 offset:8192
	ds_read_b64_tr_b16 v[174:175], v244 offset:10240
	s_waitcnt lgkmcnt(15)
	v_mfma_f32_32x32x16_bf16 v[32:47], v[80:83], v[176:179], v[32:47]
	ds_read_b128 v[148:151], v242 offset:49152
	ds_read_b128 v[152:155], v243 offset:49152
	ds_read_b64_tr_b16 v[176:177], v244 offset:8704
	ds_read_b64_tr_b16 v[178:179], v244 offset:10752
	v_exp_f32_e32 v96, v96
	v_exp_f32_e32 v97, v97
	s_waitcnt lgkmcnt(15)
	v_mfma_f32_32x32x16_bf16 v[16:31], v[80:83], v[180:183], v[16:31]
	ds_read_b64_tr_b16 v[180:181], v244 offset:9216
	ds_read_b64_tr_b16 v[182:183], v244 offset:11264
	v_exp_f32_e32 v98, v98
	v_exp_f32_e32 v99, v99
	v_mfma_f32_32x32x16_bf16 v[0:15], v[80:83], v[184:187], v[0:15]
	ds_read_b64_tr_b16 v[184:185], v244 offset:9728
	ds_read_b64_tr_b16 v[186:187], v244 offset:11776
	v_exp_f32_e32 v100, v100
	v_exp_f32_e32 v101, v101
	s_waitcnt lgkmcnt(15)
	v_mfma_f32_32x32x16_bf16 v[48:63], v[84:87], v[188:191], v[48:63]
	ds_read_b64_tr_b16 v[188:189], v244 offset:12288
	ds_read_b64_tr_b16 v[190:191], v244 offset:14336
	v_exp_f32_e32 v102, v102
	v_exp_f32_e32 v103, v103
	v_mfma_f32_32x32x16_bf16 v[32:47], v[84:87], v[204:207], v[32:47]
	ds_read_b64_tr_b16 v[204:205], v244 offset:12800
	ds_read_b64_tr_b16 v[206:207], v244 offset:14848
	v_exp_f32_e32 v104, v104
	v_exp_f32_e32 v105, v105
	v_exp_f32_e32 v106, v106
	s_waitcnt lgkmcnt(15)
	v_mfma_f32_32x32x16_bf16 v[16:31], v[84:87], v[208:211], v[16:31]
	ds_read_b64_tr_b16 v[208:209], v244 offset:13312
	ds_read_b64_tr_b16 v[210:211], v244 offset:15360
	v_exp_f32_e32 v107, v107
	v_exp_f32_e32 v108, v108
	v_exp_f32_e32 v109, v109
	v_mfma_f32_32x32x16_bf16 v[0:15], v[84:87], v[212:215], v[0:15]
	ds_read_b64_tr_b16 v[212:213], v244 offset:13824
	ds_read_b64_tr_b16 v[214:215], v244 offset:15872
	v_exp_f32_e32 v110, v110
	v_exp_f32_e32 v111, v111
	s_waitcnt vmcnt(4)
	s_waitcnt lgkmcnt(0)
	s_barrier
	v_mfma_f32_32x32x16_bf16 v[80:95], v[140:143], v[112:115], v[64:79]
	v_add_f32_e32 v136, v96, v136
	v_add_f32_e32 v137, v97, v137
	v_add_f32_e32 v136, v98, v136
	v_add_f32_e32 v137, v99, v137
	v_cvt_pk_bf16_f32 v96, v96, v97
	v_cvt_pk_bf16_f32 v97, v98, v99
	v_mfma_f32_32x32x16_bf16 v[80:95], v[144:147], v[116:119], v[80:95]
	v_add_f32_e32 v136, v100, v136
	v_add_f32_e32 v137, v101, v137
	v_add_f32_e32 v136, v102, v136
	v_add_f32_e32 v137, v103, v137
	v_cvt_pk_bf16_f32 v98, v100, v101
	v_cvt_pk_bf16_f32 v99, v102, v103
	v_mfma_f32_32x32x16_bf16 v[80:95], v[148:151], v[120:123], v[80:95]
	v_add_f32_e32 v136, v104, v136
	v_add_f32_e32 v137, v105, v137
	v_add_f32_e32 v136, v106, v136
	v_add_f32_e32 v137, v107, v137
	v_cvt_pk_bf16_f32 v100, v104, v105
	v_cvt_pk_bf16_f32 v101, v106, v107
	v_mfma_f32_32x32x16_bf16 v[80:95], v[152:155], v[124:127], v[80:95]
	v_cvt_pk_bf16_f32 v102, v108, v109
	v_cvt_pk_bf16_f32 v103, v110, v111
	v_add_f32_e32 v136, v108, v136
	v_add_f32_e32 v137, v109, v137
	v_add_f32_e32 v136, v110, v136
	v_add_f32_e32 v137, v111, v137
	v_mfma_f32_32x32x16_bf16 v[48:63], v[96:99], v[172:175], v[48:63]
	ds_read_b128 v[140:143], v240 offset:57344
	ds_read_b128 v[144:147], v241 offset:57344
	ds_read_b64_tr_b16 v[172:173], v244 offset:32768
	ds_read_b64_tr_b16 v[174:175], v244 offset:34816
	s_add_i32 m0, s25, 0x10000
	s_nop 0
	global_load_lds_dwordx4 v246, s[42:43]
	s_add_i32 m0, s25, 0x14000
	s_nop 0
	global_load_lds_dwordx4 v247, s[44:45]
	v_mfma_f32_32x32x16_bf16 v[32:47], v[96:99], v[176:179], v[32:47]
	ds_read_b128 v[148:151], v242 offset:57344
	ds_read_b128 v[152:155], v243 offset:57344
	ds_read_b64_tr_b16 v[176:177], v244 offset:33280
	ds_read_b64_tr_b16 v[178:179], v244 offset:35328
	s_add_i32 m0, s25, 0x12000
	s_nop 0
	global_load_lds_dwordx4 v248, s[42:43]
	s_add_i32 m0, s25, 0x16000
	s_nop 0
	global_load_lds_dwordx4 v249, s[44:45]
	v_exp_f32_e32 v80, v80
	v_exp_f32_e32 v81, v81
	v_mfma_f32_32x32x16_bf16 v[16:31], v[96:99], v[180:183], v[16:31]
	ds_read_b64_tr_b16 v[180:181], v244 offset:33792
	ds_read_b64_tr_b16 v[182:183], v244 offset:35840
	v_exp_f32_e32 v82, v82
	v_exp_f32_e32 v83, v83
	v_mfma_f32_32x32x16_bf16 v[0:15], v[96:99], v[184:187], v[0:15]
	ds_read_b64_tr_b16 v[184:185], v244 offset:34304
	ds_read_b64_tr_b16 v[186:187], v244 offset:36352
	v_exp_f32_e32 v84, v84
	v_exp_f32_e32 v85, v85
	v_mfma_f32_32x32x16_bf16 v[48:63], v[100:103], v[188:191], v[48:63]
	ds_read_b64_tr_b16 v[188:189], v244 offset:36864
	ds_read_b64_tr_b16 v[190:191], v244 offset:38912
	v_exp_f32_e32 v86, v86
	v_exp_f32_e32 v87, v87
	v_mfma_f32_32x32x16_bf16 v[32:47], v[100:103], v[204:207], v[32:47]
	ds_read_b64_tr_b16 v[204:205], v244 offset:37376
	ds_read_b64_tr_b16 v[206:207], v244 offset:39424
	v_exp_f32_e32 v88, v88
	v_exp_f32_e32 v89, v89
	v_exp_f32_e32 v90, v90
	v_mfma_f32_32x32x16_bf16 v[16:31], v[100:103], v[208:211], v[16:31]
	ds_read_b64_tr_b16 v[208:209], v244 offset:37888
	ds_read_b64_tr_b16 v[210:211], v244 offset:39936
	v_exp_f32_e32 v91, v91
	v_exp_f32_e32 v92, v92
	v_exp_f32_e32 v93, v93
	v_mfma_f32_32x32x16_bf16 v[0:15], v[100:103], v[212:215], v[0:15]
	ds_read_b64_tr_b16 v[212:213], v244 offset:38400
	ds_read_b64_tr_b16 v[214:215], v244 offset:40448
	v_exp_f32_e32 v94, v94
	v_exp_f32_e32 v95, v95
	s_add_u32 s42, s42, 0x4000
	s_addc_u32 s43, s43, 0
	s_add_u32 s44, s44, 0x4000
	s_addc_u32 s45, s45, 0
	s_waitcnt lgkmcnt(15)
	v_mfma_f32_32x32x16_bf16 v[96:111], v[140:143], v[112:115], v[64:79]
	v_add_f32_e32 v136, v80, v136
	v_add_f32_e32 v137, v81, v137
	v_add_f32_e32 v136, v82, v136
	v_add_f32_e32 v137, v83, v137
	v_cvt_pk_bf16_f32 v80, v80, v81
	v_cvt_pk_bf16_f32 v81, v82, v83
	v_mfma_f32_32x32x16_bf16 v[96:111], v[144:147], v[116:119], v[96:111]
	v_add_f32_e32 v136, v84, v136
	v_add_f32_e32 v137, v85, v137
	v_add_f32_e32 v136, v86, v136
	v_add_f32_e32 v137, v87, v137
	v_cvt_pk_bf16_f32 v82, v84, v85
	v_cvt_pk_bf16_f32 v83, v86, v87
	v_mfma_f32_32x32x16_bf16 v[96:111], v[148:151], v[120:123], v[96:111]
	v_add_f32_e32 v136, v88, v136
	v_add_f32_e32 v137, v89, v137
	v_add_f32_e32 v136, v90, v136
	v_add_f32_e32 v137, v91, v137
	v_cvt_pk_bf16_f32 v84, v88, v89
	v_cvt_pk_bf16_f32 v85, v90, v91
	s_waitcnt lgkmcnt(14)
	v_mfma_f32_32x32x16_bf16 v[96:111], v[152:155], v[124:127], v[96:111]
	v_cvt_pk_bf16_f32 v86, v92, v93
	v_cvt_pk_bf16_f32 v87, v94, v95
	v_add_f32_e32 v136, v92, v136
	v_add_f32_e32 v137, v93, v137
	v_add_f32_e32 v136, v94, v136
	v_add_f32_e32 v137, v95, v137
	v_mfma_f32_32x32x16_bf16 v[48:63], v[80:83], v[172:175], v[48:63]
	ds_read_b128 v[140:143], v236 offset:16384
	ds_read_b128 v[144:147], v237 offset:16384
	ds_read_b64_tr_b16 v[172:173], v244 offset:40960
	ds_read_b64_tr_b16 v[174:175], v244 offset:43008
	s_waitcnt lgkmcnt(15)
	v_mfma_f32_32x32x16_bf16 v[32:47], v[80:83], v[176:179], v[32:47]
	ds_read_b128 v[148:151], v238 offset:16384
	ds_read_b128 v[152:155], v239 offset:16384
	ds_read_b64_tr_b16 v[176:177], v244 offset:41472
	ds_read_b64_tr_b16 v[178:179], v244 offset:43520
	v_exp_f32_e32 v96, v96
	v_exp_f32_e32 v97, v97
	s_waitcnt lgkmcnt(15)
	v_mfma_f32_32x32x16_bf16 v[16:31], v[80:83], v[180:183], v[16:31]
	ds_read_b64_tr_b16 v[180:181], v244 offset:41984
	ds_read_b64_tr_b16 v[182:183], v244 offset:44032
	v_exp_f32_e32 v98, v98
	v_exp_f32_e32 v99, v99
	v_mfma_f32_32x32x16_bf16 v[0:15], v[80:83], v[184:187], v[0:15]
	ds_read_b64_tr_b16 v[184:185], v244 offset:42496
	ds_read_b64_tr_b16 v[186:187], v244 offset:44544
	v_exp_f32_e32 v100, v100
	v_exp_f32_e32 v101, v101
	s_waitcnt lgkmcnt(15)
	v_mfma_f32_32x32x16_bf16 v[48:63], v[84:87], v[188:191], v[48:63]
	ds_read_b64_tr_b16 v[188:189], v244 offset:45056
	ds_read_b64_tr_b16 v[190:191], v244 offset:47104
	v_exp_f32_e32 v102, v102
	v_exp_f32_e32 v103, v103
	v_mfma_f32_32x32x16_bf16 v[32:47], v[84:87], v[204:207], v[32:47]
	ds_read_b64_tr_b16 v[204:205], v244 offset:45568
	ds_read_b64_tr_b16 v[206:207], v244 offset:47616
	v_exp_f32_e32 v104, v104
	v_exp_f32_e32 v105, v105
	v_exp_f32_e32 v106, v106
	s_waitcnt lgkmcnt(15)
	v_mfma_f32_32x32x16_bf16 v[16:31], v[84:87], v[208:211], v[16:31]
	ds_read_b64_tr_b16 v[208:209], v244 offset:46080
	ds_read_b64_tr_b16 v[210:211], v244 offset:48128
	v_exp_f32_e32 v107, v107
	v_exp_f32_e32 v108, v108
	v_exp_f32_e32 v109, v109
	v_mfma_f32_32x32x16_bf16 v[0:15], v[84:87], v[212:215], v[0:15]
	ds_read_b64_tr_b16 v[212:213], v244 offset:46592
	ds_read_b64_tr_b16 v[214:215], v244 offset:48640
	v_exp_f32_e32 v110, v110
	v_exp_f32_e32 v111, v111
	s_add_i32 s48, s48, 1
	s_cmp_lt_u32 s48, 15
	s_cbranch_scc1 .Lda_loop
	s_waitcnt vmcnt(4)
	s_waitcnt lgkmcnt(0)
	s_barrier
	v_mfma_f32_32x32x16_bf16 v[80:95], v[140:143], v[112:115], v[64:79]
	v_add_f32_e32 v136, v96, v136
	v_add_f32_e32 v137, v97, v137
	v_add_f32_e32 v136, v98, v136
	v_add_f32_e32 v137, v99, v137
	v_cvt_pk_bf16_f32 v96, v96, v97
	v_cvt_pk_bf16_f32 v97, v98, v99
	v_mfma_f32_32x32x16_bf16 v[80:95], v[144:147], v[116:119], v[80:95]
	v_add_f32_e32 v136, v100, v136
	v_add_f32_e32 v137, v101, v137
	v_add_f32_e32 v136, v102, v136
	v_add_f32_e32 v137, v103, v137
	v_cvt_pk_bf16_f32 v98, v100, v101
	v_cvt_pk_bf16_f32 v99, v102, v103
	v_mfma_f32_32x32x16_bf16 v[80:95], v[148:151], v[120:123], v[80:95]
	v_add_f32_e32 v136, v104, v136
	v_add_f32_e32 v137, v105, v137
	v_add_f32_e32 v136, v106, v136
	v_add_f32_e32 v137, v107, v137
	v_cvt_pk_bf16_f32 v100, v104, v105
	v_cvt_pk_bf16_f32 v101, v106, v107
	v_mfma_f32_32x32x16_bf16 v[80:95], v[152:155], v[124:127], v[80:95]
	v_cvt_pk_bf16_f32 v102, v108, v109
	v_cvt_pk_bf16_f32 v103, v110, v111
	v_add_f32_e32 v136, v108, v136
	v_add_f32_e32 v137, v109, v137
	v_add_f32_e32 v136, v110, v136
	v_add_f32_e32 v137, v111, v137
	v_mfma_f32_32x32x16_bf16 v[48:63], v[96:99], v[172:175], v[48:63]
	ds_read_b128 v[140:143], v236 offset:24576
	ds_read_b128 v[144:147], v237 offset:24576
	ds_read_b64_tr_b16 v[172:173], v171 offset:0
	ds_read_b64_tr_b16 v[174:175], v171 offset:2048
	s_add_i32 m0, s25, 0x18000
	s_nop 0
	global_load_lds_dwordx4 v246, s[42:43]
	s_add_i32 m0, s25, 0x1c000
	s_nop 0
	global_load_lds_dwordx4 v247, s[44:45]
	v_mfma_f32_32x32x16_bf16 v[32:47], v[96:99], v[176:179], v[32:47]
	ds_read_b128 v[148:151], v238 offset:24576
	ds_read_b128 v[152:155], v239 offset:24576
	ds_read_b64_tr_b16 v[176:177], v171 offset:512
	ds_read_b64_tr_b16 v[178:179], v171 offset:2560
	s_add_i32 m0, s25, 0x1a000
	s_nop 0
	global_load_lds_dwordx4 v248, s[42:43]
	s_add_i32 m0, s25, 0x1e000
	s_nop 0
	global_load_lds_dwordx4 v249, s[44:45]
	v_exp_f32_e32 v80, v80
	v_exp_f32_e32 v81, v81
	v_mfma_f32_32x32x16_bf16 v[16:31], v[96:99], v[180:183], v[16:31]
	ds_read_b64_tr_b16 v[180:181], v171 offset:1024
	ds_read_b64_tr_b16 v[182:183], v171 offset:3072
	v_exp_f32_e32 v82, v82
	v_exp_f32_e32 v83, v83
	v_mfma_f32_32x32x16_bf16 v[0:15], v[96:99], v[184:187], v[0:15]
	ds_read_b64_tr_b16 v[184:185], v171 offset:1536
	ds_read_b64_tr_b16 v[186:187], v171 offset:3584
	v_exp_f32_e32 v84, v84
	v_exp_f32_e32 v85, v85
	v_mfma_f32_32x32x16_bf16 v[48:63], v[100:103], v[188:191], v[48:63]
	ds_read_b64_tr_b16 v[188:189], v171 offset:4096
	ds_read_b64_tr_b16 v[190:191], v171 offset:6144
	v_exp_f32_e32 v86, v86
	v_exp_f32_e32 v87, v87
	v_mfma_f32_32x32x16_bf16 v[32:47], v[100:103], v[204:207], v[32:47]
	ds_read_b64_tr_b16 v[204:205], v171 offset:4608
	ds_read_b64_tr_b16 v[206:207], v171 offset:6656
	v_exp_f32_e32 v88, v88
	v_exp_f32_e32 v89, v89
	v_exp_f32_e32 v90, v90
	v_mfma_f32_32x32x16_bf16 v[16:31], v[100:103], v[208:211], v[16:31]
	ds_read_b64_tr_b16 v[208:209], v171 offset:5120
	ds_read_b64_tr_b16 v[210:211], v171 offset:7168
	v_exp_f32_e32 v91, v91
	v_exp_f32_e32 v92, v92
	v_exp_f32_e32 v93, v93
	v_mfma_f32_32x32x16_bf16 v[0:15], v[100:103], v[212:215], v[0:15]
	ds_read_b64_tr_b16 v[212:213], v171 offset:5632
	ds_read_b64_tr_b16 v[214:215], v171 offset:7680
	v_exp_f32_e32 v94, v94
	v_exp_f32_e32 v95, v95
	s_add_u32 s42, s42, 0x4000
	s_addc_u32 s43, s43, 0
	s_add_u32 s44, s44, 0x4000
	s_addc_u32 s45, s45, 0
	s_waitcnt lgkmcnt(15)
	v_mfma_f32_32x32x16_bf16 v[96:111], v[140:143], v[112:115], v[64:79]
	v_add_f32_e32 v136, v80, v136
	v_add_f32_e32 v137, v81, v137
	v_add_f32_e32 v136, v82, v136
	v_add_f32_e32 v137, v83, v137
	v_cvt_pk_bf16_f32 v80, v80, v81
	v_cvt_pk_bf16_f32 v81, v82, v83
	v_mfma_f32_32x32x16_bf16 v[96:111], v[144:147], v[116:119], v[96:111]
	v_add_f32_e32 v136, v84, v136
	v_add_f32_e32 v137, v85, v137
	v_add_f32_e32 v136, v86, v136
	v_add_f32_e32 v137, v87, v137
	v_cvt_pk_bf16_f32 v82, v84, v85
	v_cvt_pk_bf16_f32 v83, v86, v87
	v_mfma_f32_32x32x16_bf16 v[96:111], v[148:151], v[120:123], v[96:111]
	v_add_f32_e32 v136, v88, v136
	v_add_f32_e32 v137, v89, v137
	v_add_f32_e32 v136, v90, v136
	v_add_f32_e32 v137, v91, v137
	v_cvt_pk_bf16_f32 v84, v88, v89
	v_cvt_pk_bf16_f32 v85, v90, v91
	s_waitcnt lgkmcnt(14)
	v_mfma_f32_32x32x16_bf16 v[96:111], v[152:155], v[124:127], v[96:111]
	v_cvt_pk_bf16_f32 v86, v92, v93
	v_cvt_pk_bf16_f32 v87, v94, v95
	v_add_f32_e32 v136, v92, v136
	v_add_f32_e32 v137, v93, v137
	v_add_f32_e32 v136, v94, v136
	v_add_f32_e32 v137, v95, v137
	v_mfma_f32_32x32x16_bf16 v[48:63], v[80:83], v[172:175], v[48:63]
	ds_read_b128 v[140:143], v236 offset:49152
	ds_read_b128 v[144:147], v237 offset:49152
	ds_read_b64_tr_b16 v[172:173], v171 offset:8192
	ds_read_b64_tr_b16 v[174:175], v171 offset:10240
	s_waitcnt lgkmcnt(15)
	v_mfma_f32_32x32x16_bf16 v[32:47], v[80:83], v[176:179], v[32:47]
	ds_read_b128 v[148:151], v238 offset:49152
	ds_read_b128 v[152:155], v239 offset:49152
	ds_read_b64_tr_b16 v[176:177], v171 offset:8704
	ds_read_b64_tr_b16 v[178:179], v171 offset:10752
	v_exp_f32_e32 v96, v96
	v_exp_f32_e32 v97, v97
	s_waitcnt lgkmcnt(15)
	v_mfma_f32_32x32x16_bf16 v[16:31], v[80:83], v[180:183], v[16:31]
	ds_read_b64_tr_b16 v[180:181], v171 offset:9216
	ds_read_b64_tr_b16 v[182:183], v171 offset:11264
	v_exp_f32_e32 v98, v98
	v_exp_f32_e32 v99, v99
	v_mfma_f32_32x32x16_bf16 v[0:15], v[80:83], v[184:187], v[0:15]
	ds_read_b64_tr_b16 v[184:185], v171 offset:9728
	ds_read_b64_tr_b16 v[186:187], v171 offset:11776
	v_exp_f32_e32 v100, v100
	v_exp_f32_e32 v101, v101
	s_waitcnt lgkmcnt(15)
	v_mfma_f32_32x32x16_bf16 v[48:63], v[84:87], v[188:191], v[48:63]
	ds_read_b64_tr_b16 v[188:189], v171 offset:12288
	ds_read_b64_tr_b16 v[190:191], v171 offset:14336
	v_exp_f32_e32 v102, v102
	v_exp_f32_e32 v103, v103
	v_mfma_f32_32x32x16_bf16 v[32:47], v[84:87], v[204:207], v[32:47]
	ds_read_b64_tr_b16 v[204:205], v171 offset:12800
	ds_read_b64_tr_b16 v[206:207], v171 offset:14848
	v_exp_f32_e32 v104, v104
	v_exp_f32_e32 v105, v105
	v_exp_f32_e32 v106, v106
	s_waitcnt lgkmcnt(15)
	v_mfma_f32_32x32x16_bf16 v[16:31], v[84:87], v[208:211], v[16:31]
	ds_read_b64_tr_b16 v[208:209], v171 offset:13312
	ds_read_b64_tr_b16 v[210:211], v171 offset:15360
	v_exp_f32_e32 v107, v107
	v_exp_f32_e32 v108, v108
	v_exp_f32_e32 v109, v109
	v_mfma_f32_32x32x16_bf16 v[0:15], v[84:87], v[212:215], v[0:15]
	ds_read_b64_tr_b16 v[212:213], v171 offset:13824
	ds_read_b64_tr_b16 v[214:215], v171 offset:15872
	v_exp_f32_e32 v110, v110
	v_exp_f32_e32 v111, v111
	s_waitcnt vmcnt(4)
	s_waitcnt lgkmcnt(0)
	s_barrier
	v_mfma_f32_32x32x16_bf16 v[80:95], v[140:143], v[112:115], v[64:79]
	v_add_f32_e32 v136, v96, v136
	v_add_f32_e32 v137, v97, v137
	v_add_f32_e32 v136, v98, v136
	v_add_f32_e32 v137, v99, v137
	v_cvt_pk_bf16_f32 v96, v96, v97
	v_cvt_pk_bf16_f32 v97, v98, v99
	v_mfma_f32_32x32x16_bf16 v[80:95], v[144:147], v[116:119], v[80:95]
	v_add_f32_e32 v136, v100, v136
	v_add_f32_e32 v137, v101, v137
	v_add_f32_e32 v136, v102, v136
	v_add_f32_e32 v137, v103, v137
	v_cvt_pk_bf16_f32 v98, v100, v101
	v_cvt_pk_bf16_f32 v99, v102, v103
	v_mfma_f32_32x32x16_bf16 v[80:95], v[148:151], v[120:123], v[80:95]
	v_add_f32_e32 v136, v104, v136
	v_add_f32_e32 v137, v105, v137
	v_add_f32_e32 v136, v106, v136
	v_add_f32_e32 v137, v107, v137
	v_cvt_pk_bf16_f32 v100, v104, v105
	v_cvt_pk_bf16_f32 v101, v106, v107
	v_mfma_f32_32x32x16_bf16 v[80:95], v[152:155], v[124:127], v[80:95]
	v_cvt_pk_bf16_f32 v102, v108, v109
	v_cvt_pk_bf16_f32 v103, v110, v111
	v_add_f32_e32 v136, v108, v136
	v_add_f32_e32 v137, v109, v137
	v_add_f32_e32 v136, v110, v136
	v_add_f32_e32 v137, v111, v137
	v_mfma_f32_32x32x16_bf16 v[48:63], v[96:99], v[172:175], v[48:63]
	ds_read_b128 v[140:143], v236 offset:57344
	ds_read_b128 v[144:147], v237 offset:57344
	ds_read_b64_tr_b16 v[172:173], v171 offset:32768
	ds_read_b64_tr_b16 v[174:175], v171 offset:34816
	v_mfma_f32_32x32x16_bf16 v[32:47], v[96:99], v[176:179], v[32:47]
	ds_read_b128 v[148:151], v238 offset:57344
	ds_read_b128 v[152:155], v239 offset:57344
	ds_read_b64_tr_b16 v[176:177], v171 offset:33280
	ds_read_b64_tr_b16 v[178:179], v171 offset:35328
	v_exp_f32_e32 v80, v80
	v_exp_f32_e32 v81, v81
	v_mfma_f32_32x32x16_bf16 v[16:31], v[96:99], v[180:183], v[16:31]
	ds_read_b64_tr_b16 v[180:181], v171 offset:33792
	ds_read_b64_tr_b16 v[182:183], v171 offset:35840
	v_exp_f32_e32 v82, v82
	v_exp_f32_e32 v83, v83
	v_mfma_f32_32x32x16_bf16 v[0:15], v[96:99], v[184:187], v[0:15]
	ds_read_b64_tr_b16 v[184:185], v171 offset:34304
	ds_read_b64_tr_b16 v[186:187], v171 offset:36352
	v_exp_f32_e32 v84, v84
	v_exp_f32_e32 v85, v85
	v_mfma_f32_32x32x16_bf16 v[48:63], v[100:103], v[188:191], v[48:63]
	ds_read_b64_tr_b16 v[188:189], v171 offset:36864
	ds_read_b64_tr_b16 v[190:191], v171 offset:38912
	v_exp_f32_e32 v86, v86
	v_exp_f32_e32 v87, v87
	v_mfma_f32_32x32x16_bf16 v[32:47], v[100:103], v[204:207], v[32:47]
	ds_read_b64_tr_b16 v[204:205], v171 offset:37376
	ds_read_b64_tr_b16 v[206:207], v171 offset:39424
	v_exp_f32_e32 v88, v88
	v_exp_f32_e32 v89, v89
	v_exp_f32_e32 v90, v90
	v_mfma_f32_32x32x16_bf16 v[16:31], v[100:103], v[208:211], v[16:31]
	ds_read_b64_tr_b16 v[208:209], v171 offset:37888
	ds_read_b64_tr_b16 v[210:211], v171 offset:39936
	v_exp_f32_e32 v91, v91
	v_exp_f32_e32 v92, v92
	v_exp_f32_e32 v93, v93
	v_mfma_f32_32x32x16_bf16 v[0:15], v[100:103], v[212:215], v[0:15]
	ds_read_b64_tr_b16 v[212:213], v171 offset:38400
	ds_read_b64_tr_b16 v[214:215], v171 offset:40448
	v_exp_f32_e32 v94, v94
	v_exp_f32_e32 v95, v95
	s_waitcnt lgkmcnt(15)
	v_mfma_f32_32x32x16_bf16 v[96:111], v[140:143], v[112:115], v[64:79]
	v_add_f32_e32 v136, v80, v136
	v_add_f32_e32 v137, v81, v137
	v_add_f32_e32 v136, v82, v136
	v_add_f32_e32 v137, v83, v137
	v_cvt_pk_bf16_f32 v80, v80, v81
	v_cvt_pk_bf16_f32 v81, v82, v83
	v_mfma_f32_32x32x16_bf16 v[96:111], v[144:147], v[116:119], v[96:111]
	v_add_f32_e32 v136, v84, v136
	v_add_f32_e32 v137, v85, v137
	v_add_f32_e32 v136, v86, v136
	v_add_f32_e32 v137, v87, v137
	v_cvt_pk_bf16_f32 v82, v84, v85
	v_cvt_pk_bf16_f32 v83, v86, v87
	v_mfma_f32_32x32x16_bf16 v[96:111], v[148:151], v[120:123], v[96:111]
	v_add_f32_e32 v136, v88, v136
	v_add_f32_e32 v137, v89, v137
	v_add_f32_e32 v136, v90, v136
	v_add_f32_e32 v137, v91, v137
	v_cvt_pk_bf16_f32 v84, v88, v89
	v_cvt_pk_bf16_f32 v85, v90, v91
	s_waitcnt lgkmcnt(14)
	v_mfma_f32_32x32x16_bf16 v[96:111], v[152:155], v[124:127], v[96:111]
	v_cvt_pk_bf16_f32 v86, v92, v93
	v_cvt_pk_bf16_f32 v87, v94, v95
	v_add_f32_e32 v136, v92, v136
	v_add_f32_e32 v137, v93, v137
	v_add_f32_e32 v136, v94, v136
	v_add_f32_e32 v137, v95, v137
	v_mfma_f32_32x32x16_bf16 v[48:63], v[80:83], v[172:175], v[48:63]
	ds_read_b128 v[140:143], v240 offset:16384
	ds_read_b128 v[144:147], v241 offset:16384
	ds_read_b64_tr_b16 v[172:173], v171 offset:40960
	ds_read_b64_tr_b16 v[174:175], v171 offset:43008
	s_waitcnt lgkmcnt(15)
	v_mfma_f32_32x32x16_bf16 v[32:47], v[80:83], v[176:179], v[32:47]
	ds_read_b128 v[148:151], v242 offset:16384
	ds_read_b128 v[152:155], v243 offset:16384
	ds_read_b64_tr_b16 v[176:177], v171 offset:41472
	ds_read_b64_tr_b16 v[178:179], v171 offset:43520
	v_exp_f32_e32 v96, v96
	v_exp_f32_e32 v97, v97
	s_waitcnt lgkmcnt(15)
	v_mfma_f32_32x32x16_bf16 v[16:31], v[80:83], v[180:183], v[16:31]
	ds_read_b64_tr_b16 v[180:181], v171 offset:41984
	ds_read_b64_tr_b16 v[182:183], v171 offset:44032
	v_exp_f32_e32 v98, v98
	v_exp_f32_e32 v99, v99
	v_mfma_f32_32x32x16_bf16 v[0:15], v[80:83], v[184:187], v[0:15]
	ds_read_b64_tr_b16 v[184:185], v171 offset:42496
	ds_read_b64_tr_b16 v[186:187], v171 offset:44544
	v_exp_f32_e32 v100, v100
	v_exp_f32_e32 v101, v101
	s_waitcnt lgkmcnt(15)
	v_mfma_f32_32x32x16_bf16 v[48:63], v[84:87], v[188:191], v[48:63]
	ds_read_b64_tr_b16 v[188:189], v171 offset:45056
	ds_read_b64_tr_b16 v[190:191], v171 offset:47104
	v_exp_f32_e32 v102, v102
	v_exp_f32_e32 v103, v103
	v_mfma_f32_32x32x16_bf16 v[32:47], v[84:87], v[204:207], v[32:47]
	ds_read_b64_tr_b16 v[204:205], v171 offset:45568
	ds_read_b64_tr_b16 v[206:207], v171 offset:47616
	v_exp_f32_e32 v104, v104
	v_exp_f32_e32 v105, v105
	v_exp_f32_e32 v106, v106
	s_waitcnt lgkmcnt(15)
	v_mfma_f32_32x32x16_bf16 v[16:31], v[84:87], v[208:211], v[16:31]
	ds_read_b64_tr_b16 v[208:209], v171 offset:46080
	ds_read_b64_tr_b16 v[210:211], v171 offset:48128
	v_exp_f32_e32 v107, v107
	v_exp_f32_e32 v108, v108
	v_exp_f32_e32 v109, v109
	v_mfma_f32_32x32x16_bf16 v[0:15], v[84:87], v[212:215], v[0:15]
	ds_read_b64_tr_b16 v[212:213], v171 offset:46592
	ds_read_b64_tr_b16 v[214:215], v171 offset:48640
	v_exp_f32_e32 v110, v110
	v_exp_f32_e32 v111, v111
	s_waitcnt vmcnt(0)
	s_waitcnt lgkmcnt(0)
	s_barrier
	v_mfma_f32_32x32x16_bf16 v[80:95], v[140:143], v[112:115], v[64:79]
	v_add_f32_e32 v136, v96, v136
	v_add_f32_e32 v137, v97, v137
	v_add_f32_e32 v136, v98, v136
	v_add_f32_e32 v137, v99, v137
	v_cvt_pk_bf16_f32 v96, v96, v97
	v_cvt_pk_bf16_f32 v97, v98, v99
	v_mfma_f32_32x32x16_bf16 v[80:95], v[144:147], v[116:119], v[80:95]
	v_add_f32_e32 v136, v100, v136
	v_add_f32_e32 v137, v101, v137
	v_add_f32_e32 v136, v102, v136
	v_add_f32_e32 v137, v103, v137
	v_cvt_pk_bf16_f32 v98, v100, v101
	v_cvt_pk_bf16_f32 v99, v102, v103
	v_mfma_f32_32x32x16_bf16 v[80:95], v[148:151], v[120:123], v[80:95]
	v_add_f32_e32 v136, v104, v136
	v_add_f32_e32 v137, v105, v137
	v_add_f32_e32 v136, v106, v136
	v_add_f32_e32 v137, v107, v137
	v_cvt_pk_bf16_f32 v100, v104, v105
	v_cvt_pk_bf16_f32 v101, v106, v107
	v_mfma_f32_32x32x16_bf16 v[80:95], v[152:155], v[124:127], v[80:95]
	v_cvt_pk_bf16_f32 v102, v108, v109
	v_cvt_pk_bf16_f32 v103, v110, v111
	v_add_f32_e32 v136, v108, v136
	v_add_f32_e32 v137, v109, v137
	v_add_f32_e32 v136, v110, v136
	v_add_f32_e32 v137, v111, v137
	v_mfma_f32_32x32x16_bf16 v[48:63], v[96:99], v[172:175], v[48:63]
	ds_read_b128 v[140:143], v240 offset:24576
	ds_read_b128 v[144:147], v241 offset:24576
	ds_read_b64_tr_b16 v[172:173], v244 offset:0
	ds_read_b64_tr_b16 v[174:175], v244 offset:2048
	v_mfma_f32_32x32x16_bf16 v[32:47], v[96:99], v[176:179], v[32:47]
	ds_read_b128 v[148:151], v242 offset:24576
	ds_read_b128 v[152:155], v243 offset:24576
	ds_read_b64_tr_b16 v[176:177], v244 offset:512
	ds_read_b64_tr_b16 v[178:179], v244 offset:2560
	v_exp_f32_e32 v80, v80
	v_exp_f32_e32 v81, v81
	v_mfma_f32_32x32x16_bf16 v[16:31], v[96:99], v[180:183], v[16:31]
	ds_read_b64_tr_b16 v[180:181], v244 offset:1024
	ds_read_b64_tr_b16 v[182:183], v244 offset:3072
	v_exp_f32_e32 v82, v82
	v_exp_f32_e32 v83, v83
	v_mfma_f32_32x32x16_bf16 v[0:15], v[96:99], v[184:187], v[0:15]
	ds_read_b64_tr_b16 v[184:185], v244 offset:1536
	ds_read_b64_tr_b16 v[186:187], v244 offset:3584
	v_exp_f32_e32 v84, v84
	v_exp_f32_e32 v85, v85
	v_mfma_f32_32x32x16_bf16 v[48:63], v[100:103], v[188:191], v[48:63]
	ds_read_b64_tr_b16 v[188:189], v244 offset:4096
	ds_read_b64_tr_b16 v[190:191], v244 offset:6144
	v_exp_f32_e32 v86, v86
	v_exp_f32_e32 v87, v87
	v_mfma_f32_32x32x16_bf16 v[32:47], v[100:103], v[204:207], v[32:47]
	ds_read_b64_tr_b16 v[204:205], v244 offset:4608
	ds_read_b64_tr_b16 v[206:207], v244 offset:6656
	v_exp_f32_e32 v88, v88
	v_exp_f32_e32 v89, v89
	v_exp_f32_e32 v90, v90
	v_mfma_f32_32x32x16_bf16 v[16:31], v[100:103], v[208:211], v[16:31]
	ds_read_b64_tr_b16 v[208:209], v244 offset:5120
	ds_read_b64_tr_b16 v[210:211], v244 offset:7168
	v_exp_f32_e32 v91, v91
	v_exp_f32_e32 v92, v92
	v_exp_f32_e32 v93, v93
	v_mfma_f32_32x32x16_bf16 v[0:15], v[100:103], v[212:215], v[0:15]
	ds_read_b64_tr_b16 v[212:213], v244 offset:5632
	ds_read_b64_tr_b16 v[214:215], v244 offset:7680
	v_exp_f32_e32 v94, v94
	v_exp_f32_e32 v95, v95
	s_waitcnt lgkmcnt(15)
	v_mfma_f32_32x32x16_bf16 v[96:111], v[140:143], v[112:115], v[64:79]
	v_add_f32_e32 v136, v80, v136
	v_add_f32_e32 v137, v81, v137
	v_add_f32_e32 v136, v82, v136
	v_add_f32_e32 v137, v83, v137
	v_cvt_pk_bf16_f32 v80, v80, v81
	v_cvt_pk_bf16_f32 v81, v82, v83
	v_mfma_f32_32x32x16_bf16 v[96:111], v[144:147], v[116:119], v[96:111]
	v_add_f32_e32 v136, v84, v136
	v_add_f32_e32 v137, v85, v137
	v_add_f32_e32 v136, v86, v136
	v_add_f32_e32 v137, v87, v137
	v_cvt_pk_bf16_f32 v82, v84, v85
	v_cvt_pk_bf16_f32 v83, v86, v87
	v_mfma_f32_32x32x16_bf16 v[96:111], v[148:151], v[120:123], v[96:111]
	v_add_f32_e32 v136, v88, v136
	v_add_f32_e32 v137, v89, v137
	v_add_f32_e32 v136, v90, v136
	v_add_f32_e32 v137, v91, v137
	v_cvt_pk_bf16_f32 v84, v88, v89
	v_cvt_pk_bf16_f32 v85, v90, v91
	s_waitcnt lgkmcnt(14)
	v_mfma_f32_32x32x16_bf16 v[96:111], v[152:155], v[124:127], v[96:111]
	v_cvt_pk_bf16_f32 v86, v92, v93
	v_cvt_pk_bf16_f32 v87, v94, v95
	v_add_f32_e32 v136, v92, v136
	v_add_f32_e32 v137, v93, v137
	v_add_f32_e32 v136, v94, v136
	v_add_f32_e32 v137, v95, v137
	v_mfma_f32_32x32x16_bf16 v[48:63], v[80:83], v[172:175], v[48:63]
	ds_read_b128 v[140:143], v240 offset:49152
	ds_read_b128 v[144:147], v241 offset:49152
	ds_read_b64_tr_b16 v[172:173], v244 offset:8192
	ds_read_b64_tr_b16 v[174:175], v244 offset:10240
	s_waitcnt lgkmcnt(15)
	v_mfma_f32_32x32x16_bf16 v[32:47], v[80:83], v[176:179], v[32:47]
	ds_read_b128 v[148:151], v242 offset:49152
	ds_read_b128 v[152:155], v243 offset:49152
	ds_read_b64_tr_b16 v[176:177], v244 offset:8704
	ds_read_b64_tr_b16 v[178:179], v244 offset:10752
	v_exp_f32_e32 v96, v96
	v_exp_f32_e32 v97, v97
	s_waitcnt lgkmcnt(15)
	v_mfma_f32_32x32x16_bf16 v[16:31], v[80:83], v[180:183], v[16:31]
	ds_read_b64_tr_b16 v[180:181], v244 offset:9216
	ds_read_b64_tr_b16 v[182:183], v244 offset:11264
	v_exp_f32_e32 v98, v98
	v_exp_f32_e32 v99, v99
	v_mfma_f32_32x32x16_bf16 v[0:15], v[80:83], v[184:187], v[0:15]
	ds_read_b64_tr_b16 v[184:185], v244 offset:9728
	ds_read_b64_tr_b16 v[186:187], v244 offset:11776
	v_exp_f32_e32 v100, v100
	v_exp_f32_e32 v101, v101
	s_waitcnt lgkmcnt(15)
	v_mfma_f32_32x32x16_bf16 v[48:63], v[84:87], v[188:191], v[48:63]
	ds_read_b64_tr_b16 v[188:189], v244 offset:12288
	ds_read_b64_tr_b16 v[190:191], v244 offset:14336
	v_exp_f32_e32 v102, v102
	v_exp_f32_e32 v103, v103
	v_mfma_f32_32x32x16_bf16 v[32:47], v[84:87], v[204:207], v[32:47]
	ds_read_b64_tr_b16 v[204:205], v244 offset:12800
	ds_read_b64_tr_b16 v[206:207], v244 offset:14848
	v_exp_f32_e32 v104, v104
	v_exp_f32_e32 v105, v105
	v_exp_f32_e32 v106, v106
	s_waitcnt lgkmcnt(15)
	v_mfma_f32_32x32x16_bf16 v[16:31], v[84:87], v[208:211], v[16:31]
	ds_read_b64_tr_b16 v[208:209], v244 offset:13312
	ds_read_b64_tr_b16 v[210:211], v244 offset:15360
	v_exp_f32_e32 v107, v107
	v_exp_f32_e32 v108, v108
	v_exp_f32_e32 v109, v109
	v_mfma_f32_32x32x16_bf16 v[0:15], v[84:87], v[212:215], v[0:15]
	ds_read_b64_tr_b16 v[212:213], v244 offset:13824
	ds_read_b64_tr_b16 v[214:215], v244 offset:15872
	v_exp_f32_e32 v110, v110
	v_exp_f32_e32 v111, v111
	s_waitcnt vmcnt(0)
	s_waitcnt lgkmcnt(0)
	s_barrier
	v_mfma_f32_32x32x16_bf16 v[80:95], v[140:143], v[112:115], v[64:79]
	v_add_f32_e32 v136, v96, v136
	v_add_f32_e32 v137, v97, v137
	v_add_f32_e32 v136, v98, v136
	v_add_f32_e32 v137, v99, v137
	v_cvt_pk_bf16_f32 v96, v96, v97
	v_cvt_pk_bf16_f32 v97, v98, v99
	v_mfma_f32_32x32x16_bf16 v[80:95], v[144:147], v[116:119], v[80:95]
	v_add_f32_e32 v136, v100, v136
	v_add_f32_e32 v137, v101, v137
	v_add_f32_e32 v136, v102, v136
	v_add_f32_e32 v137, v103, v137
	v_cvt_pk_bf16_f32 v98, v100, v101
	v_cvt_pk_bf16_f32 v99, v102, v103
	v_mfma_f32_32x32x16_bf16 v[80:95], v[148:151], v[120:123], v[80:95]
	v_add_f32_e32 v136, v104, v136
	v_add_f32_e32 v137, v105, v137
	v_add_f32_e32 v136, v106, v136
	v_add_f32_e32 v137, v107, v137
	v_cvt_pk_bf16_f32 v100, v104, v105
	v_cvt_pk_bf16_f32 v101, v106, v107
	v_mfma_f32_32x32x16_bf16 v[80:95], v[152:155], v[124:127], v[80:95]
	v_cvt_pk_bf16_f32 v102, v108, v109
	v_cvt_pk_bf16_f32 v103, v110, v111
	v_add_f32_e32 v136, v108, v136
	v_add_f32_e32 v137, v109, v137
	v_add_f32_e32 v136, v110, v136
	v_add_f32_e32 v137, v111, v137
	v_mfma_f32_32x32x16_bf16 v[48:63], v[96:99], v[172:175], v[48:63]
	ds_read_b128 v[140:143], v240 offset:57344
	ds_read_b128 v[144:147], v241 offset:57344
	ds_read_b64_tr_b16 v[172:173], v244 offset:32768
	ds_read_b64_tr_b16 v[174:175], v244 offset:34816
	v_mfma_f32_32x32x16_bf16 v[32:47], v[96:99], v[176:179], v[32:47]
	ds_read_b128 v[148:151], v242 offset:57344
	ds_read_b128 v[152:155], v243 offset:57344
	ds_read_b64_tr_b16 v[176:177], v244 offset:33280
	ds_read_b64_tr_b16 v[178:179], v244 offset:35328
	v_exp_f32_e32 v80, v80
	v_exp_f32_e32 v81, v81
	v_mfma_f32_32x32x16_bf16 v[16:31], v[96:99], v[180:183], v[16:31]
	ds_read_b64_tr_b16 v[180:181], v244 offset:33792
	ds_read_b64_tr_b16 v[182:183], v244 offset:35840
	v_exp_f32_e32 v82, v82
	v_exp_f32_e32 v83, v83
	v_mfma_f32_32x32x16_bf16 v[0:15], v[96:99], v[184:187], v[0:15]
	ds_read_b64_tr_b16 v[184:185], v244 offset:34304
	ds_read_b64_tr_b16 v[186:187], v244 offset:36352
	v_exp_f32_e32 v84, v84
	v_exp_f32_e32 v85, v85
	v_mfma_f32_32x32x16_bf16 v[48:63], v[100:103], v[188:191], v[48:63]
	ds_read_b64_tr_b16 v[188:189], v244 offset:36864
	ds_read_b64_tr_b16 v[190:191], v244 offset:38912
	v_exp_f32_e32 v86, v86
	v_exp_f32_e32 v87, v87
	v_mfma_f32_32x32x16_bf16 v[32:47], v[100:103], v[204:207], v[32:47]
	ds_read_b64_tr_b16 v[204:205], v244 offset:37376
	ds_read_b64_tr_b16 v[206:207], v244 offset:39424
	v_exp_f32_e32 v88, v88
	v_exp_f32_e32 v89, v89
	v_exp_f32_e32 v90, v90
	v_mfma_f32_32x32x16_bf16 v[16:31], v[100:103], v[208:211], v[16:31]
	ds_read_b64_tr_b16 v[208:209], v244 offset:37888
	ds_read_b64_tr_b16 v[210:211], v244 offset:39936
	v_exp_f32_e32 v91, v91
	v_exp_f32_e32 v92, v92
	v_exp_f32_e32 v93, v93
	v_mfma_f32_32x32x16_bf16 v[0:15], v[100:103], v[212:215], v[0:15]
	ds_read_b64_tr_b16 v[212:213], v244 offset:38400
	ds_read_b64_tr_b16 v[214:215], v244 offset:40448
	v_exp_f32_e32 v94, v94
	v_exp_f32_e32 v95, v95
	s_waitcnt lgkmcnt(15)
	v_mfma_f32_32x32x16_bf16 v[96:111], v[140:143], v[112:115], v[64:79]
	v_add_f32_e32 v136, v80, v136
	v_add_f32_e32 v137, v81, v137
	v_add_f32_e32 v136, v82, v136
	v_add_f32_e32 v137, v83, v137
	v_cvt_pk_bf16_f32 v80, v80, v81
	v_cvt_pk_bf16_f32 v81, v82, v83
	v_mfma_f32_32x32x16_bf16 v[96:111], v[144:147], v[116:119], v[96:111]
	v_add_f32_e32 v136, v84, v136
	v_add_f32_e32 v137, v85, v137
	v_add_f32_e32 v136, v86, v136
	v_add_f32_e32 v137, v87, v137
	v_cvt_pk_bf16_f32 v82, v84, v85
	v_cvt_pk_bf16_f32 v83, v86, v87
	v_mfma_f32_32x32x16_bf16 v[96:111], v[148:151], v[120:123], v[96:111]
	v_add_f32_e32 v136, v88, v136
	v_add_f32_e32 v137, v89, v137
	v_add_f32_e32 v136, v90, v136
	v_add_f32_e32 v137, v91, v137
	v_cvt_pk_bf16_f32 v84, v88, v89
	v_cvt_pk_bf16_f32 v85, v90, v91
	s_waitcnt lgkmcnt(14)
	v_mfma_f32_32x32x16_bf16 v[96:111], v[152:155], v[124:127], v[96:111]
	v_cvt_pk_bf16_f32 v86, v92, v93
	v_cvt_pk_bf16_f32 v87, v94, v95
	v_add_f32_e32 v136, v92, v136
	v_add_f32_e32 v137, v93, v137
	v_add_f32_e32 v136, v94, v136
	v_add_f32_e32 v137, v95, v137
	v_mfma_f32_32x32x16_bf16 v[48:63], v[80:83], v[172:175], v[48:63]
	ds_read_b64_tr_b16 v[172:173], v244 offset:40960
	ds_read_b64_tr_b16 v[174:175], v244 offset:43008
	s_waitcnt lgkmcnt(14)
	v_mfma_f32_32x32x16_bf16 v[32:47], v[80:83], v[176:179], v[32:47]
	ds_read_b64_tr_b16 v[176:177], v244 offset:41472
	ds_read_b64_tr_b16 v[178:179], v244 offset:43520
	v_exp_f32_e32 v96, v96
	v_exp_f32_e32 v97, v97
	s_waitcnt lgkmcnt(14)
	v_mfma_f32_32x32x16_bf16 v[16:31], v[80:83], v[180:183], v[16:31]
	ds_read_b64_tr_b16 v[180:181], v244 offset:41984
	ds_read_b64_tr_b16 v[182:183], v244 offset:44032
	v_exp_f32_e32 v98, v98
	v_exp_f32_e32 v99, v99
	s_waitcnt lgkmcnt(14)
	v_mfma_f32_32x32x16_bf16 v[0:15], v[80:83], v[184:187], v[0:15]
	ds_read_b64_tr_b16 v[184:185], v244 offset:42496
	ds_read_b64_tr_b16 v[186:187], v244 offset:44544
	v_exp_f32_e32 v100, v100
	v_exp_f32_e32 v101, v101
	s_waitcnt lgkmcnt(14)
	v_mfma_f32_32x32x16_bf16 v[48:63], v[84:87], v[188:191], v[48:63]
	ds_read_b64_tr_b16 v[188:189], v244 offset:45056
	ds_read_b64_tr_b16 v[190:191], v244 offset:47104
	v_exp_f32_e32 v102, v102
	v_exp_f32_e32 v103, v103
	s_waitcnt lgkmcnt(14)
	v_mfma_f32_32x32x16_bf16 v[32:47], v[84:87], v[204:207], v[32:47]
	ds_read_b64_tr_b16 v[204:205], v244 offset:45568
	ds_read_b64_tr_b16 v[206:207], v244 offset:47616
	v_exp_f32_e32 v104, v104
	v_exp_f32_e32 v105, v105
	v_exp_f32_e32 v106, v106
	s_waitcnt lgkmcnt(14)
	v_mfma_f32_32x32x16_bf16 v[16:31], v[84:87], v[208:211], v[16:31]
	ds_read_b64_tr_b16 v[208:209], v244 offset:46080
	ds_read_b64_tr_b16 v[210:211], v244 offset:48128
	v_exp_f32_e32 v107, v107
	v_exp_f32_e32 v108, v108
	v_exp_f32_e32 v109, v109
	s_waitcnt lgkmcnt(14)
	v_mfma_f32_32x32x16_bf16 v[0:15], v[84:87], v[212:215], v[0:15]
	ds_read_b64_tr_b16 v[212:213], v244 offset:46592
	ds_read_b64_tr_b16 v[214:215], v244 offset:48640
	v_exp_f32_e32 v110, v110
	v_exp_f32_e32 v111, v111
	s_waitcnt lgkmcnt(0)
	v_add_f32_e32 v136, v96, v136
	v_add_f32_e32 v137, v97, v137
	v_add_f32_e32 v136, v98, v136
	v_add_f32_e32 v137, v99, v137
	v_cvt_pk_bf16_f32 v96, v96, v97
	v_cvt_pk_bf16_f32 v97, v98, v99
	v_add_f32_e32 v136, v100, v136
	v_add_f32_e32 v137, v101, v137
	v_add_f32_e32 v136, v102, v136
	v_add_f32_e32 v137, v103, v137
	v_cvt_pk_bf16_f32 v98, v100, v101
	v_cvt_pk_bf16_f32 v99, v102, v103
	v_add_f32_e32 v136, v104, v136
	v_add_f32_e32 v137, v105, v137
	v_add_f32_e32 v136, v106, v136
	v_add_f32_e32 v137, v107, v137
	v_cvt_pk_bf16_f32 v100, v104, v105
	v_cvt_pk_bf16_f32 v101, v106, v107
	v_cvt_pk_bf16_f32 v102, v108, v109
	v_cvt_pk_bf16_f32 v103, v110, v111
	v_add_f32_e32 v136, v108, v136
	v_add_f32_e32 v137, v109, v137
	v_add_f32_e32 v136, v110, v136
	v_add_f32_e32 v137, v111, v137
	v_add_f32_e32 v136, v137, v136
	s_nop 1
	v_mfma_f32_32x32x16_bf16 v[48:63], v[96:99], v[172:175], v[48:63]
	v_mfma_f32_32x32x16_bf16 v[32:47], v[96:99], v[176:179], v[32:47]
	v_mfma_f32_32x32x16_bf16 v[16:31], v[96:99], v[180:183], v[16:31]
	v_mfma_f32_32x32x16_bf16 v[0:15], v[96:99], v[184:187], v[0:15]
	v_mfma_f32_32x32x16_bf16 v[48:63], v[100:103], v[188:191], v[48:63]
	v_mfma_f32_32x32x16_bf16 v[32:47], v[100:103], v[204:207], v[32:47]
	v_mfma_f32_32x32x16_bf16 v[16:31], v[100:103], v[208:211], v[16:31]
	v_mfma_f32_32x32x16_bf16 v[0:15], v[100:103], v[212:215], v[0:15]
	s_branch .LBB0_482
